# ret_sample: q/k staging loads hoisted above the state loads (counted vmcnt keeps state loads in flight); on top of v26
# speedup vs baseline: 1.0011x; 1.0011x over previous
; __device__ __forceinline__ float bflo(unsigned u) { return __uint_as_float(u << 16); }
; __device__ __forceinline__ float ret_lg(int h) { return log1pf(-exp2f(-5.0f - (float)h)); }
; __device__ __forceinline__ void mix_ret_sample(const Params& p, LAS unsigned char* lds, int u) {
;     ...
;   const float lg = ret_lg(h);
;   const int r0 = TOKP + 8 * b;
;   f32x4 s0v[16];
;   {
;     const float* S0p = p.in[3] + ((size_t)(b * 8 + h) * 128 + 16 * w) * 256 + 4 * lane;
; #pragma unroll
;     for (int dd = 0; dd < 16; ++dd) s0v[dd] = __builtin_nontemporal_load((const f32x4*)(S0p + dd * 256));
;   }
;   __syncthreads();
;   for (int idx = tid; idx < 1024; idx += 512) {
;     const int i = idx >> 7, d = idx & 127;
;     qT[d * 8 + i] = bflo((unsigned)RQ[(size_t)(r0 + i) * 1024 + h * 128 + d]);
;     kT[d * 8 + i] = bflo((unsigned)RK[(size_t)(r0 + i) * 1024 + h * 128 + d]) * __expf((float)(7 - i) * lg);
;   }
.LBB0_232:
	s_andn2_b64 vcc, exec, s[36:37]
	s_cbranch_vccnz .LBB0_241
	s_nop 0
	v_cvt_f32_u32_e32 v0, s43
	s_mov_b32 s35, 0xc2fc0000
	s_lshl_b32 s29, s44, 3
	s_or_b32 s34, s29, s43
	v_sub_f32_e32 v0, 0xc0a00000, v0
	v_cmp_gt_f32_e32 vcc, s35, v0
	s_and_b64 s[36:37], vcc, exec
	s_cselect_b32 s35, 0xffffffc0, 0
	v_cndmask_b32_e32 v1, 0, v236, vcc
	v_add_f32_e32 v0, v0, v1
	v_exp_f32_e32 v0, v0
	v_mov_b32_e32 v69, v226
	v_readlane_b32 s36, v255, 1
	v_ldexp_f32 v2, v0, s35
	v_sub_f32_e32 v3, 1.0, v2
	v_add_f32_e32 v0, -1.0, v3
	v_sub_f32_e32 v1, v0, v3
	v_add_f32_e32 v1, 1.0, v1
	v_sub_f32_e64 v0, -v2, v0
	v_add_f32_e32 v4, v0, v1
	v_frexp_mant_f32_e32 v0, v3
	s_mov_b32 s35, 0x3f2aaaab
	v_cmp_gt_f32_e32 vcc, s35, v0
	v_cvt_f64_f32_e32 v[0:1], v3
	v_frexp_exp_i32_f64_e32 v0, v[0:1]
	v_subbrev_co_u32_e32 v0, vcc, 0, v0, vcc
	v_sub_u32_e32 v1, 0, v0
	v_ldexp_f32 v3, v3, v1
	v_ldexp_f32 v1, v4, v1
	v_add_f32_e32 v4, -1.0, v3
	v_add_f32_e32 v5, 1.0, v4
	v_sub_f32_e32 v5, v3, v5
	v_add_f32_e32 v5, v1, v5
	v_add_f32_e32 v6, v4, v5
	v_sub_f32_e32 v4, v6, v4
	v_sub_f32_e32 v4, v5, v4
	v_add_f32_e32 v5, 1.0, v3
	v_add_f32_e32 v7, -1.0, v5
	v_sub_f32_e32 v3, v3, v7
	v_add_f32_e32 v1, v1, v3
	v_add_f32_e32 v3, v5, v1
	v_sub_f32_e32 v5, v3, v5
	v_sub_f32_e32 v1, v1, v5
	v_rcp_f32_e32 v5, v3
	v_cvt_f32_i32_e32 v0, v0
	s_mov_b32 s35, 0x3f317218
	v_cmp_nlt_f32_e32 vcc, 1.0, v2
	v_mul_f32_e32 v7, v6, v5
	v_mul_f32_e32 v8, v3, v7
	v_fma_f32 v9, v7, v3, -v8
	v_fmac_f32_e32 v9, v7, v1
	v_add_f32_e32 v10, v8, v9
	v_sub_f32_e32 v11, v6, v10
	v_sub_f32_e32 v6, v6, v11
	v_sub_f32_e32 v8, v10, v8
	v_sub_f32_e32 v6, v6, v10
	v_add_f32_e32 v4, v4, v6
	v_sub_f32_e32 v6, v8, v9
	v_add_f32_e32 v4, v6, v4
	v_add_f32_e32 v6, v11, v4
	v_mul_f32_e32 v8, v5, v6
	v_mul_f32_e32 v9, v3, v8
	v_fma_f32 v3, v8, v3, -v9
	v_fmac_f32_e32 v3, v8, v1
	v_sub_f32_e32 v1, v11, v6
	v_add_f32_e32 v1, v4, v1
	v_add_f32_e32 v4, v9, v3
	v_sub_f32_e32 v10, v6, v4
	v_sub_f32_e32 v6, v6, v10
	v_sub_f32_e32 v9, v4, v9
	v_sub_f32_e32 v4, v6, v4
	v_add_f32_e32 v1, v1, v4
	v_sub_f32_e32 v3, v9, v3
	v_add_f32_e32 v1, v3, v1
	v_add_f32_e32 v3, v7, v8
	v_add_f32_e32 v1, v10, v1
	v_sub_f32_e32 v4, v3, v7
	v_mul_f32_e32 v1, v5, v1
	v_sub_f32_e32 v4, v8, v4
	v_add_f32_e32 v1, v4, v1
	v_mul_f32_e32 v7, 0x3f317218, v0
	v_add_f32_e32 v4, v3, v1
	v_fma_f32 v8, v0, s35, -v7
	v_mul_f32_e32 v5, v4, v4
	v_fmac_f32_e32 v8, 0xb102e308, v0
	v_sub_f32_e32 v0, v4, v3
	v_fmamk_f32 v6, v5, 0x3e9b6dac, v229
	v_sub_f32_e32 v0, v1, v0
	v_add_f32_e32 v1, v7, v8
	v_fmaak_f32 v6, v5, v6, 0x3f2aaada
	v_sub_f32_e32 v3, v1, v7
	v_ldexp_f32 v7, v4, 1
	v_mul_f32_e32 v4, v4, v5
	v_mul_f32_e32 v4, v4, v6
	v_add_f32_e32 v5, v7, v4
	v_sub_f32_e32 v6, v5, v7
	v_ldexp_f32 v0, v0, 1
	v_sub_f32_e32 v4, v4, v6
	v_add_f32_e32 v0, v0, v4
	v_add_f32_e32 v4, v5, v0
	v_sub_f32_e32 v5, v4, v5
	v_sub_f32_e32 v0, v0, v5
	v_add_f32_e32 v5, v1, v4
	v_sub_f32_e32 v6, v5, v1
	v_sub_f32_e32 v7, v5, v6
	v_sub_f32_e32 v3, v8, v3
	v_sub_f32_e32 v1, v1, v7
	v_sub_f32_e32 v4, v4, v6
	v_add_f32_e32 v1, v4, v1
	v_add_f32_e32 v4, v3, v0
	v_sub_f32_e32 v6, v4, v3
	v_sub_f32_e32 v7, v4, v6
	v_sub_f32_e32 v3, v3, v7
	v_sub_f32_e32 v0, v0, v6
	v_add_f32_e32 v1, v4, v1
	v_add_f32_e32 v0, v0, v3
	v_add_f32_e32 v3, v5, v1
	v_sub_f32_e32 v4, v3, v5
	v_sub_f32_e32 v1, v1, v4
	v_add_f32_e32 v0, v0, v1
	v_add_f32_e32 v0, v3, v0
	v_cndmask_b32_e32 v0, v250, v0, vcc
	v_cmp_neq_f32_e32 vcc, 1.0, v2
	s_mov_b32 s35, 0x33800000
	v_ashrrev_i32_e32 v103, 6, v69
	v_cndmask_b32_e32 v0, v231, v0, vcc
	v_cmp_gt_f32_e32 vcc, s35, v2
	v_readlane_b32 s37, v255, 2
	s_mov_b32 s35, s37
	v_cndmask_b32_e64 v106, v0, -v2, vcc
	v_lshlrev_b32_e32 v0, 4, v103
	s_lshl_b32 s34, s34, 7
	v_ashrrev_i32_e32 v1, 31, v0
	v_lshl_add_u64 v[66:67], v[0:1], 0, s[34:35]
	v_lshlrev_b32_e32 v2, 2, v69
	v_lshlrev_b64 v[0:1], 10, v[66:67]
	v_and_b32_e32 v70, 0xfc, v2
	v_lshl_add_u64 v[0:1], s[10:11], 0, v[0:1]
	v_lshlrev_b32_e32 v64, 2, v70
	v_lshl_add_u64 v[0:1], v[0:1], 0, v[64:65]
	s_movk_i32 s34, 0x1000
	v_add_co_u32_e32 v2, vcc, s34, v0
	s_movk_i32 s34, 0x2000
	s_nop 0
	v_addc_co_u32_e32 v3, vcc, 0, v1, vcc
	v_add_co_u32_e32 v4, vcc, s34, v0
	s_lshl_b32 s35, s44, 3
	s_or_b32 s35, s35, 0x2000
	v_and_b32_e32 v200, 0x7f, v69
	v_ashrrev_i32_e32 v201, 7, v69
	v_add_u32_e32 v202, s35, v201
	v_lshlrev_b32_e32 v202, 11, v202
	v_lshl_or_b32 v203, s43, 7, v200
	v_lshl_add_u32 v202, v203, 1, v202
	v_add_u32_e32 v203, 0x2000, v202
	global_load_ushort v204, v202, s[64:65]
	global_load_ushort v205, v202, s[96:97]
	global_load_ushort v206, v203, s[64:65]
	global_load_ushort v207, v203, s[96:97]
	global_load_dwordx4 v[60:63], v[0:1], off nt
	global_load_dwordx4 v[56:59], v[0:1], off offset:1024 nt
	global_load_dwordx4 v[52:55], v[0:1], off offset:2048 nt
	global_load_dwordx4 v[48:51], v[0:1], off offset:3072 nt
	v_addc_co_u32_e32 v5, vcc, 0, v1, vcc
	global_load_dwordx4 v[44:47], v[4:5], off offset:-4096 nt
	global_load_dwordx4 v[40:43], v[2:3], off offset:1024 nt
	global_load_dwordx4 v[36:39], v[2:3], off offset:2048 nt
	global_load_dwordx4 v[32:35], v[2:3], off offset:3072 nt
	global_load_dwordx4 v[28:31], v[4:5], off nt
	global_load_dwordx4 v[24:27], v[4:5], off offset:1024 nt
	global_load_dwordx4 v[20:23], v[4:5], off offset:2048 nt
	global_load_dwordx4 v[16:19], v[4:5], off offset:3072 nt
	v_add_co_u32_e32 v0, vcc, 0x3000, v0
	s_and_b32 s34, s29, 0x3f8
	s_nop 0
	v_addc_co_u32_e32 v1, vcc, 0, v1, vcc
	global_load_dwordx4 v[12:15], v[0:1], off nt
	global_load_dwordx4 v[8:11], v[0:1], off offset:1024 nt
	global_load_dwordx4 v[4:7], v[0:1], off offset:2048 nt
	s_nop 0
	global_load_dwordx4 v[0:3], v[0:1], off offset:3072 nt
	s_movk_i32 s35, 0x400
	s_mov_b32 s41, s37
	s_or_b32 s29, s34, 0x2000
	v_cmp_gt_i32_e32 vcc, s35, v69
	s_barrier
	s_and_saveexec_b64 s[36:37], vcc
	s_cbranch_execz .LBB0_236
	v_sub_u32_e32 v208, 7, v201
	v_cvt_f32_u32_e32 v208, v208
	v_mul_f32_e32 v208, v106, v208
	v_mul_f32_e32 v208, 0x3fb8aa3b, v208
	v_exp_f32_e32 v208, v208
	v_sub_u32_e32 v209, 3, v201
	v_cvt_f32_u32_e32 v209, v209
	v_mul_f32_e32 v209, v106, v209
	v_mul_f32_e32 v209, 0x3fb8aa3b, v209
	v_exp_f32_e32 v209, v209
	v_lshl_add_u32 v210, v200, 3, v201
	v_lshlrev_b32_e32 v210, 2, v210
	v_add_u32_e32 v211, 16, v210
	s_waitcnt vmcnt(16)
	v_lshlrev_b32_e32 v204, 16, v204
	v_lshlrev_b32_e32 v205, 16, v205
	v_lshlrev_b32_e32 v206, 16, v206
	v_lshlrev_b32_e32 v207, 16, v207
	v_mul_f32_e32 v205, v208, v205
	v_mul_f32_e32 v207, v209, v207
	ds_write2st64_b32 v210, v204, v205 offset1:16
	ds_write2st64_b32 v211, v206, v207 offset1:16
